# P7 epilogue: counted vmcnt waits per 16-row group before the residual adds instead of one vmcnt(0) per half; on top of v36
# baseline (speedup 1.0000x reference)
;     __device__ __forceinline__ void operator()(const f32x4 (&acc)[2][2][4][2], const pg8::Unit& u, int wr, int wc, int fr, int fq) const {
;         const int row0 = u.pm * 256 + wr * 64 + fr; const int colb = u.pn * 256 + 32 * wc + 8 * fq;
;         if (u.nt == 0) {
; #pragma unroll
;             for (int ai = 0; ai < 2; ++ai) {
;                 f32x4 xv[4][2][2];
; #pragma unroll
;                 for (int m = 0; m < 4; ++m)
; #pragma unroll
;                     for (int bj = 0; bj < 2; ++bj) { const float* xr = out + (size_t)(row0 + ai * 128 + m * 16) * DM + colb + 128 * bj; xv[m][bj][0] = *(const f32x4*)xr; xv[m][bj][1] = *(const f32x4*)(xr + 4); }
; #pragma unroll
;                 for (int m = 0; m < 4; ++m) {
;                     float* orow = out + (size_t)(row0 + ai * 128 + m * 16) * DM;
; #pragma unroll
;                     for (int bj = 0; bj < 2; ++bj) {
;                         const int col = colb + 128 * bj;
;                         *(f32x4*)(orow + col) = acc[ai][bj][m][0] + xv[m][bj][0]; *(f32x4*)(orow + col + 4) = acc[ai][bj][m][1] + xv[m][bj][1];
;                     }
;                 }
;             }
.LBB0_809:
	v_readlane_b32 s18, v254, 30
	v_readlane_b32 s19, v254, 31
	v_bfe_u32 v150, v148, 3, 1
	v_and_b32_e32 v148, 0xfffffff7, v148
	v_lshl_add_u32 v142, v150, 2, v142
	v_lshlrev_b64 v[142:143], 2, v[142:143]
	v_lshlrev_b64 v[146:147], 13, v[148:149]
	v_lshl_add_u64 v[144:145], s[18:19], 0, v[142:143]
	v_lshl_add_u64 v[146:147], v[144:145], 0, v[146:147]
	s_mov_b32 s5, 0
	v_mov_b32_e32 v222, v124
	v_mov_b32_e32 v223, v125
	v_mov_b32_e32 v224, v126
	v_mov_b32_e32 v225, v127
	v_mov_b32_dpp v124, v120 row_ror:8 row_mask:0xf bank_mask:0xc
	v_mov_b32_dpp v125, v121 row_ror:8 row_mask:0xf bank_mask:0xc
	v_mov_b32_dpp v126, v122 row_ror:8 row_mask:0xf bank_mask:0xc
	v_mov_b32_dpp v127, v123 row_ror:8 row_mask:0xf bank_mask:0xc
	v_mov_b32_dpp v120, v222 row_ror:8 row_mask:0xf bank_mask:0x3
	v_mov_b32_dpp v121, v223 row_ror:8 row_mask:0xf bank_mask:0x3
	v_mov_b32_dpp v122, v224 row_ror:8 row_mask:0xf bank_mask:0x3
	v_mov_b32_dpp v123, v225 row_ror:8 row_mask:0xf bank_mask:0x3
	v_mov_b32_e32 v142, v116
	v_mov_b32_e32 v143, v117
	v_mov_b32_e32 v144, v118
	v_mov_b32_e32 v145, v119
	v_mov_b32_dpp v116, v112 row_ror:8 row_mask:0xf bank_mask:0xc
	v_mov_b32_dpp v117, v113 row_ror:8 row_mask:0xf bank_mask:0xc
	v_mov_b32_dpp v118, v114 row_ror:8 row_mask:0xf bank_mask:0xc
	v_mov_b32_dpp v119, v115 row_ror:8 row_mask:0xf bank_mask:0xc
	v_mov_b32_dpp v112, v142 row_ror:8 row_mask:0xf bank_mask:0x3
	v_mov_b32_dpp v113, v143 row_ror:8 row_mask:0xf bank_mask:0x3
	v_mov_b32_dpp v114, v144 row_ror:8 row_mask:0xf bank_mask:0x3
	v_mov_b32_dpp v115, v145 row_ror:8 row_mask:0xf bank_mask:0x3
	v_mov_b32_e32 v222, v108
	v_mov_b32_e32 v223, v109
	v_mov_b32_e32 v224, v110
	v_mov_b32_e32 v225, v111
	v_mov_b32_dpp v108, v104 row_ror:8 row_mask:0xf bank_mask:0xc
	v_mov_b32_dpp v109, v105 row_ror:8 row_mask:0xf bank_mask:0xc
	v_mov_b32_dpp v110, v106 row_ror:8 row_mask:0xf bank_mask:0xc
	v_mov_b32_dpp v111, v107 row_ror:8 row_mask:0xf bank_mask:0xc
	v_mov_b32_dpp v104, v222 row_ror:8 row_mask:0xf bank_mask:0x3
	v_mov_b32_dpp v105, v223 row_ror:8 row_mask:0xf bank_mask:0x3
	v_mov_b32_dpp v106, v224 row_ror:8 row_mask:0xf bank_mask:0x3
	v_mov_b32_dpp v107, v225 row_ror:8 row_mask:0xf bank_mask:0x3
	v_mov_b32_e32 v142, v100
	v_mov_b32_e32 v143, v101
	v_mov_b32_e32 v144, v102
	v_mov_b32_e32 v145, v103
	v_mov_b32_dpp v100, v96 row_ror:8 row_mask:0xf bank_mask:0xc
	v_mov_b32_dpp v101, v97 row_ror:8 row_mask:0xf bank_mask:0xc
	v_mov_b32_dpp v102, v98 row_ror:8 row_mask:0xf bank_mask:0xc
	v_mov_b32_dpp v103, v99 row_ror:8 row_mask:0xf bank_mask:0xc
	v_mov_b32_dpp v96, v142 row_ror:8 row_mask:0xf bank_mask:0x3
	v_mov_b32_dpp v97, v143 row_ror:8 row_mask:0xf bank_mask:0x3
	v_mov_b32_dpp v98, v144 row_ror:8 row_mask:0xf bank_mask:0x3
	v_mov_b32_dpp v99, v145 row_ror:8 row_mask:0xf bank_mask:0x3
	v_mov_b32_e32 v222, v92
	v_mov_b32_e32 v223, v93
	v_mov_b32_e32 v224, v94
	v_mov_b32_e32 v225, v95
	v_mov_b32_dpp v92, v88 row_ror:8 row_mask:0xf bank_mask:0xc
	v_mov_b32_dpp v93, v89 row_ror:8 row_mask:0xf bank_mask:0xc
	v_mov_b32_dpp v94, v90 row_ror:8 row_mask:0xf bank_mask:0xc
	v_mov_b32_dpp v95, v91 row_ror:8 row_mask:0xf bank_mask:0xc
	v_mov_b32_dpp v88, v222 row_ror:8 row_mask:0xf bank_mask:0x3
	v_mov_b32_dpp v89, v223 row_ror:8 row_mask:0xf bank_mask:0x3
	v_mov_b32_dpp v90, v224 row_ror:8 row_mask:0xf bank_mask:0x3
	v_mov_b32_dpp v91, v225 row_ror:8 row_mask:0xf bank_mask:0x3
	v_mov_b32_e32 v142, v84
	v_mov_b32_e32 v143, v85
	v_mov_b32_e32 v144, v86
	v_mov_b32_e32 v145, v87
	v_mov_b32_dpp v84, v80 row_ror:8 row_mask:0xf bank_mask:0xc
	v_mov_b32_dpp v85, v81 row_ror:8 row_mask:0xf bank_mask:0xc
	v_mov_b32_dpp v86, v82 row_ror:8 row_mask:0xf bank_mask:0xc
	v_mov_b32_dpp v87, v83 row_ror:8 row_mask:0xf bank_mask:0xc
	v_mov_b32_dpp v80, v142 row_ror:8 row_mask:0xf bank_mask:0x3
	v_mov_b32_dpp v81, v143 row_ror:8 row_mask:0xf bank_mask:0x3
	v_mov_b32_dpp v82, v144 row_ror:8 row_mask:0xf bank_mask:0x3
	v_mov_b32_dpp v83, v145 row_ror:8 row_mask:0xf bank_mask:0x3
	v_mov_b32_e32 v222, v76
	v_mov_b32_e32 v223, v77
	v_mov_b32_e32 v224, v78
	v_mov_b32_e32 v225, v79
	v_mov_b32_dpp v76, v72 row_ror:8 row_mask:0xf bank_mask:0xc
	v_mov_b32_dpp v77, v73 row_ror:8 row_mask:0xf bank_mask:0xc
	v_mov_b32_dpp v78, v74 row_ror:8 row_mask:0xf bank_mask:0xc
	v_mov_b32_dpp v79, v75 row_ror:8 row_mask:0xf bank_mask:0xc
	v_mov_b32_dpp v72, v222 row_ror:8 row_mask:0xf bank_mask:0x3
	v_mov_b32_dpp v73, v223 row_ror:8 row_mask:0xf bank_mask:0x3
	v_mov_b32_dpp v74, v224 row_ror:8 row_mask:0xf bank_mask:0x3
	v_mov_b32_dpp v75, v225 row_ror:8 row_mask:0xf bank_mask:0x3
	v_mov_b32_e32 v142, v68
	v_mov_b32_e32 v143, v69
	v_mov_b32_e32 v144, v70
	v_mov_b32_e32 v145, v71
	v_mov_b32_dpp v68, v64 row_ror:8 row_mask:0xf bank_mask:0xc
	v_mov_b32_dpp v69, v65 row_ror:8 row_mask:0xf bank_mask:0xc
	v_mov_b32_dpp v70, v66 row_ror:8 row_mask:0xf bank_mask:0xc
	v_mov_b32_dpp v71, v67 row_ror:8 row_mask:0xf bank_mask:0xc
	v_mov_b32_dpp v64, v142 row_ror:8 row_mask:0xf bank_mask:0x3
	v_mov_b32_dpp v65, v143 row_ror:8 row_mask:0xf bank_mask:0x3
	v_mov_b32_dpp v66, v144 row_ror:8 row_mask:0xf bank_mask:0x3
	v_mov_b32_dpp v67, v145 row_ror:8 row_mask:0xf bank_mask:0x3
	v_mov_b32_e32 v222, v60
	v_mov_b32_e32 v223, v61
	v_mov_b32_e32 v224, v62
	v_mov_b32_e32 v225, v63
	v_mov_b32_dpp v60, v56 row_ror:8 row_mask:0xf bank_mask:0xc
	v_mov_b32_dpp v61, v57 row_ror:8 row_mask:0xf bank_mask:0xc
	v_mov_b32_dpp v62, v58 row_ror:8 row_mask:0xf bank_mask:0xc
	v_mov_b32_dpp v63, v59 row_ror:8 row_mask:0xf bank_mask:0xc
	v_mov_b32_dpp v56, v222 row_ror:8 row_mask:0xf bank_mask:0x3
	v_mov_b32_dpp v57, v223 row_ror:8 row_mask:0xf bank_mask:0x3
;     __device__ __forceinline__ void operator()(const f32x4 (&acc)[2][2][4][2], const pg8::Unit& u, int wr, int wc, int fr, int fq) const {
;         const int row0 = u.pm * 256 + wr * 64 + fr; const int colb = u.pn * 256 + 32 * wc + 8 * fq;
;         if (u.nt == 0) {
; #pragma unroll
;             for (int ai = 0; ai < 2; ++ai) {
;                 f32x4 xv[4][2][2];
; #pragma unroll
;                 for (int m = 0; m < 4; ++m)
; #pragma unroll
;                     for (int bj = 0; bj < 2; ++bj) { const float* xr = out + (size_t)(row0 + ai * 128 + m * 16) * DM + colb + 128 * bj; xv[m][bj][0] = *(const f32x4*)xr; xv[m][bj][1] = *(const f32x4*)(xr + 4); }
; #pragma unroll
;                 for (int m = 0; m < 4; ++m) {
;                     float* orow = out + (size_t)(row0 + ai * 128 + m * 16) * DM;
; #pragma unroll
;                     for (int bj = 0; bj < 2; ++bj) {
;                         const int col = colb + 128 * bj;
;                         *(f32x4*)(orow + col) = acc[ai][bj][m][0] + xv[m][bj][0]; *(f32x4*)(orow + col + 4) = acc[ai][bj][m][1] + xv[m][bj][1];
;                     }
;                 }
;             }
	v_mov_b32_dpp v58, v224 row_ror:8 row_mask:0xf bank_mask:0x3
	v_mov_b32_dpp v59, v225 row_ror:8 row_mask:0xf bank_mask:0x3
	v_mov_b32_e32 v142, v52
	v_mov_b32_e32 v143, v53
	v_mov_b32_e32 v144, v54
	v_mov_b32_e32 v145, v55
	v_mov_b32_dpp v52, v48 row_ror:8 row_mask:0xf bank_mask:0xc
	v_mov_b32_dpp v53, v49 row_ror:8 row_mask:0xf bank_mask:0xc
	v_mov_b32_dpp v54, v50 row_ror:8 row_mask:0xf bank_mask:0xc
	v_mov_b32_dpp v55, v51 row_ror:8 row_mask:0xf bank_mask:0xc
	v_mov_b32_dpp v48, v142 row_ror:8 row_mask:0xf bank_mask:0x3
	v_mov_b32_dpp v49, v143 row_ror:8 row_mask:0xf bank_mask:0x3
	v_mov_b32_dpp v50, v144 row_ror:8 row_mask:0xf bank_mask:0x3
	v_mov_b32_dpp v51, v145 row_ror:8 row_mask:0xf bank_mask:0x3
	v_mov_b32_e32 v222, v44
	v_mov_b32_e32 v223, v45
	v_mov_b32_e32 v224, v46
	v_mov_b32_e32 v225, v47
	v_mov_b32_dpp v44, v40 row_ror:8 row_mask:0xf bank_mask:0xc
	v_mov_b32_dpp v45, v41 row_ror:8 row_mask:0xf bank_mask:0xc
	v_mov_b32_dpp v46, v42 row_ror:8 row_mask:0xf bank_mask:0xc
	v_mov_b32_dpp v47, v43 row_ror:8 row_mask:0xf bank_mask:0xc
	v_mov_b32_dpp v40, v222 row_ror:8 row_mask:0xf bank_mask:0x3
	v_mov_b32_dpp v41, v223 row_ror:8 row_mask:0xf bank_mask:0x3
	v_mov_b32_dpp v42, v224 row_ror:8 row_mask:0xf bank_mask:0x3
	v_mov_b32_dpp v43, v225 row_ror:8 row_mask:0xf bank_mask:0x3
	v_mov_b32_e32 v142, v36
	v_mov_b32_e32 v143, v37
	v_mov_b32_e32 v144, v38
	v_mov_b32_e32 v145, v39
	v_mov_b32_dpp v36, v32 row_ror:8 row_mask:0xf bank_mask:0xc
	v_mov_b32_dpp v37, v33 row_ror:8 row_mask:0xf bank_mask:0xc
	v_mov_b32_dpp v38, v34 row_ror:8 row_mask:0xf bank_mask:0xc
	v_mov_b32_dpp v39, v35 row_ror:8 row_mask:0xf bank_mask:0xc
	v_mov_b32_dpp v32, v142 row_ror:8 row_mask:0xf bank_mask:0x3
	v_mov_b32_dpp v33, v143 row_ror:8 row_mask:0xf bank_mask:0x3
	v_mov_b32_dpp v34, v144 row_ror:8 row_mask:0xf bank_mask:0x3
	v_mov_b32_dpp v35, v145 row_ror:8 row_mask:0xf bank_mask:0x3
	v_mov_b32_e32 v222, v28
	v_mov_b32_e32 v223, v29
	v_mov_b32_e32 v224, v30
	v_mov_b32_e32 v225, v31
	v_mov_b32_dpp v28, v24 row_ror:8 row_mask:0xf bank_mask:0xc
	v_mov_b32_dpp v29, v25 row_ror:8 row_mask:0xf bank_mask:0xc
	v_mov_b32_dpp v30, v26 row_ror:8 row_mask:0xf bank_mask:0xc
	v_mov_b32_dpp v31, v27 row_ror:8 row_mask:0xf bank_mask:0xc
	v_mov_b32_dpp v24, v222 row_ror:8 row_mask:0xf bank_mask:0x3
	v_mov_b32_dpp v25, v223 row_ror:8 row_mask:0xf bank_mask:0x3
	v_mov_b32_dpp v26, v224 row_ror:8 row_mask:0xf bank_mask:0x3
	v_mov_b32_dpp v27, v225 row_ror:8 row_mask:0xf bank_mask:0x3
	v_mov_b32_e32 v142, v20
	v_mov_b32_e32 v143, v21
	v_mov_b32_e32 v144, v22
	v_mov_b32_e32 v145, v23
	v_mov_b32_dpp v20, v16 row_ror:8 row_mask:0xf bank_mask:0xc
	v_mov_b32_dpp v21, v17 row_ror:8 row_mask:0xf bank_mask:0xc
	v_mov_b32_dpp v22, v18 row_ror:8 row_mask:0xf bank_mask:0xc
	v_mov_b32_dpp v23, v19 row_ror:8 row_mask:0xf bank_mask:0xc
	v_mov_b32_dpp v16, v142 row_ror:8 row_mask:0xf bank_mask:0x3
	v_mov_b32_dpp v17, v143 row_ror:8 row_mask:0xf bank_mask:0x3
	v_mov_b32_dpp v18, v144 row_ror:8 row_mask:0xf bank_mask:0x3
	v_mov_b32_dpp v19, v145 row_ror:8 row_mask:0xf bank_mask:0x3
	v_mov_b32_e32 v222, v12
	v_mov_b32_e32 v223, v13
	v_mov_b32_e32 v224, v14
	v_mov_b32_e32 v225, v15
	v_mov_b32_dpp v12, v8 row_ror:8 row_mask:0xf bank_mask:0xc
	v_mov_b32_dpp v13, v9 row_ror:8 row_mask:0xf bank_mask:0xc
	v_mov_b32_dpp v14, v10 row_ror:8 row_mask:0xf bank_mask:0xc
	v_mov_b32_dpp v15, v11 row_ror:8 row_mask:0xf bank_mask:0xc
	v_mov_b32_dpp v8, v222 row_ror:8 row_mask:0xf bank_mask:0x3
	v_mov_b32_dpp v9, v223 row_ror:8 row_mask:0xf bank_mask:0x3
	v_mov_b32_dpp v10, v224 row_ror:8 row_mask:0xf bank_mask:0x3
	v_mov_b32_dpp v11, v225 row_ror:8 row_mask:0xf bank_mask:0x3
	v_mov_b32_e32 v142, v4
	v_mov_b32_e32 v143, v5
	v_mov_b32_e32 v144, v6
	v_mov_b32_e32 v145, v7
	v_mov_b32_dpp v4, v0 row_ror:8 row_mask:0xf bank_mask:0xc
	v_mov_b32_dpp v5, v1 row_ror:8 row_mask:0xf bank_mask:0xc
	v_mov_b32_dpp v6, v2 row_ror:8 row_mask:0xf bank_mask:0xc
	v_mov_b32_dpp v7, v3 row_ror:8 row_mask:0xf bank_mask:0xc
	v_mov_b32_dpp v0, v142 row_ror:8 row_mask:0xf bank_mask:0x3
	v_mov_b32_dpp v1, v143 row_ror:8 row_mask:0xf bank_mask:0x3
	v_mov_b32_dpp v2, v144 row_ror:8 row_mask:0xf bank_mask:0x3
	v_mov_b32_dpp v3, v145 row_ror:8 row_mask:0xf bank_mask:0x3
	s_mov_b32 s4, 0x0
	v_lshl_add_u64 v[224:225], v[146:147], 0, s[4:5]
	global_load_dwordx4 v[160:163], v[224:225], off
	global_load_dwordx4 v[168:171], v[224:225], off offset:512
	s_mov_b32 s4, 0x10000
	v_lshl_add_u64 v[226:227], v[146:147], 0, s[4:5]
	global_load_dwordx4 v[164:167], v[226:227], off
	global_load_dwordx4 v[172:175], v[226:227], off offset:512
	s_mov_b32 s4, 0x20000
	v_lshl_add_u64 v[224:225], v[146:147], 0, s[4:5]
	global_load_dwordx4 v[176:179], v[224:225], off
	global_load_dwordx4 v[184:187], v[224:225], off offset:512
	s_mov_b32 s4, 0x30000
	v_lshl_add_u64 v[226:227], v[146:147], 0, s[4:5]
	global_load_dwordx4 v[180:183], v[226:227], off
	global_load_dwordx4 v[190:193], v[226:227], off offset:512
	s_mov_b32 s4, 0x40000
	v_lshl_add_u64 v[224:225], v[146:147], 0, s[4:5]
	global_load_dwordx4 v[194:197], v[224:225], off
	global_load_dwordx4 v[202:205], v[224:225], off offset:512
	s_mov_b32 s4, 0x50000
	v_lshl_add_u64 v[226:227], v[146:147], 0, s[4:5]
	global_load_dwordx4 v[198:201], v[226:227], off
	global_load_dwordx4 v[206:209], v[226:227], off offset:512
	s_mov_b32 s4, 0x60000
	v_lshl_add_u64 v[224:225], v[146:147], 0, s[4:5]
	global_load_dwordx4 v[210:213], v[224:225], off
	global_load_dwordx4 v[218:221], v[224:225], off offset:512
	s_mov_b32 s4, 0x70000
	v_lshl_add_u64 v[226:227], v[146:147], 0, s[4:5]
	global_load_dwordx4 v[214:217], v[226:227], off
	global_load_dwordx4 v[150:153], v[226:227], off offset:512
	s_waitcnt vmcnt(12)
;     __device__ __forceinline__ void operator()(const f32x4 (&acc)[2][2][4][2], const pg8::Unit& u, int wr, int wc, int fr, int fq) const {
;         const int row0 = u.pm * 256 + wr * 64 + fr; const int colb = u.pn * 256 + 32 * wc + 8 * fq;
;         if (u.nt == 0) {
; #pragma unroll
;             for (int ai = 0; ai < 2; ++ai) {
;                 f32x4 xv[4][2][2];
; #pragma unroll
;                 for (int m = 0; m < 4; ++m)
; #pragma unroll
;                     for (int bj = 0; bj < 2; ++bj) { const float* xr = out + (size_t)(row0 + ai * 128 + m * 16) * DM + colb + 128 * bj; xv[m][bj][0] = *(const f32x4*)xr; xv[m][bj][1] = *(const f32x4*)(xr + 4); }
; #pragma unroll
;                 for (int m = 0; m < 4; ++m) {
;                     float* orow = out + (size_t)(row0 + ai * 128 + m * 16) * DM;
; #pragma unroll
;                     for (int bj = 0; bj < 2; ++bj) {
;                         const int col = colb + 128 * bj;
;                         *(f32x4*)(orow + col) = acc[ai][bj][m][0] + xv[m][bj][0]; *(f32x4*)(orow + col + 4) = acc[ai][bj][m][1] + xv[m][bj][1];
;                     }
;                 }
;             }
	v_pk_add_f32 v[124:125], v[124:125], v[160:161]
	v_pk_add_f32 v[126:127], v[126:127], v[162:163]
	v_pk_add_f32 v[120:121], v[120:121], v[164:165]
	v_pk_add_f32 v[122:123], v[122:123], v[166:167]
	v_pk_add_f32 v[116:117], v[116:117], v[168:169]
	v_pk_add_f32 v[118:119], v[118:119], v[170:171]
	v_pk_add_f32 v[112:113], v[112:113], v[172:173]
	v_pk_add_f32 v[114:115], v[114:115], v[174:175]
	s_waitcnt vmcnt(8)
	v_pk_add_f32 v[108:109], v[108:109], v[176:177]
	v_pk_add_f32 v[110:111], v[110:111], v[178:179]
	v_pk_add_f32 v[104:105], v[104:105], v[180:181]
	v_pk_add_f32 v[106:107], v[106:107], v[182:183]
	v_pk_add_f32 v[100:101], v[100:101], v[184:185]
	v_pk_add_f32 v[102:103], v[102:103], v[186:187]
	v_pk_add_f32 v[96:97], v[96:97], v[190:191]
	v_pk_add_f32 v[98:99], v[98:99], v[192:193]
	s_waitcnt vmcnt(4)
	v_pk_add_f32 v[92:93], v[92:93], v[194:195]
	v_pk_add_f32 v[94:95], v[94:95], v[196:197]
	v_pk_add_f32 v[88:89], v[88:89], v[198:199]
	v_pk_add_f32 v[90:91], v[90:91], v[200:201]
	v_pk_add_f32 v[84:85], v[84:85], v[202:203]
	v_pk_add_f32 v[86:87], v[86:87], v[204:205]
	v_pk_add_f32 v[80:81], v[80:81], v[206:207]
	v_pk_add_f32 v[82:83], v[82:83], v[208:209]
	s_waitcnt vmcnt(0)
	v_pk_add_f32 v[76:77], v[76:77], v[210:211]
	v_pk_add_f32 v[78:79], v[78:79], v[212:213]
	v_pk_add_f32 v[72:73], v[72:73], v[214:215]
	v_pk_add_f32 v[74:75], v[74:75], v[216:217]
	v_pk_add_f32 v[68:69], v[68:69], v[218:219]
	v_pk_add_f32 v[70:71], v[70:71], v[220:221]
	v_pk_add_f32 v[64:65], v[64:65], v[150:151]
	v_pk_add_f32 v[66:67], v[66:67], v[152:153]
	s_mov_b32 s4, 0x0
	v_lshl_add_u64 v[224:225], v[146:147], 0, s[4:5]
	global_store_dwordx4 v[224:225], v[124:127], off
	global_store_dwordx4 v[224:225], v[116:119], off offset:512
	s_mov_b32 s4, 0x10000
	v_lshl_add_u64 v[226:227], v[146:147], 0, s[4:5]
	global_store_dwordx4 v[226:227], v[120:123], off
	global_store_dwordx4 v[226:227], v[112:115], off offset:512
	s_mov_b32 s4, 0x20000
	v_lshl_add_u64 v[224:225], v[146:147], 0, s[4:5]
	global_store_dwordx4 v[224:225], v[108:111], off
	global_store_dwordx4 v[224:225], v[100:103], off offset:512
	s_mov_b32 s4, 0x30000
	v_lshl_add_u64 v[226:227], v[146:147], 0, s[4:5]
	global_store_dwordx4 v[226:227], v[104:107], off
	global_store_dwordx4 v[226:227], v[96:99], off offset:512
	s_mov_b32 s4, 0x40000
	v_lshl_add_u64 v[224:225], v[146:147], 0, s[4:5]
	global_store_dwordx4 v[224:225], v[92:95], off
	global_store_dwordx4 v[224:225], v[84:87], off offset:512
	s_mov_b32 s4, 0x50000
	v_lshl_add_u64 v[226:227], v[146:147], 0, s[4:5]
	global_store_dwordx4 v[226:227], v[88:91], off
	global_store_dwordx4 v[226:227], v[80:83], off offset:512
	s_mov_b32 s4, 0x60000
	v_lshl_add_u64 v[224:225], v[146:147], 0, s[4:5]
	global_store_dwordx4 v[224:225], v[76:79], off
	global_store_dwordx4 v[224:225], v[68:71], off offset:512
	s_mov_b32 s4, 0x70000
	v_lshl_add_u64 v[226:227], v[146:147], 0, s[4:5]
	global_store_dwordx4 v[226:227], v[72:75], off
	global_store_dwordx4 v[226:227], v[64:67], off offset:512
	s_mov_b32 s4, 0x100000
	v_lshl_add_u64 v[224:225], v[146:147], 0, s[4:5]
	global_load_dwordx4 v[160:163], v[224:225], off
	global_load_dwordx4 v[168:171], v[224:225], off offset:512
	s_mov_b32 s4, 0x110000
	v_lshl_add_u64 v[226:227], v[146:147], 0, s[4:5]
	global_load_dwordx4 v[164:167], v[226:227], off
	global_load_dwordx4 v[172:175], v[226:227], off offset:512
	s_mov_b32 s4, 0x120000
	v_lshl_add_u64 v[224:225], v[146:147], 0, s[4:5]
	global_load_dwordx4 v[176:179], v[224:225], off
	global_load_dwordx4 v[184:187], v[224:225], off offset:512
	s_mov_b32 s4, 0x130000
	v_lshl_add_u64 v[226:227], v[146:147], 0, s[4:5]
	global_load_dwordx4 v[180:183], v[226:227], off
	global_load_dwordx4 v[190:193], v[226:227], off offset:512
	s_mov_b32 s4, 0x140000
	v_lshl_add_u64 v[224:225], v[146:147], 0, s[4:5]
	global_load_dwordx4 v[194:197], v[224:225], off
	global_load_dwordx4 v[202:205], v[224:225], off offset:512
	s_mov_b32 s4, 0x150000
	v_lshl_add_u64 v[226:227], v[146:147], 0, s[4:5]
	global_load_dwordx4 v[198:201], v[226:227], off
	global_load_dwordx4 v[206:209], v[226:227], off offset:512
	s_mov_b32 s4, 0x160000
	v_lshl_add_u64 v[224:225], v[146:147], 0, s[4:5]
	global_load_dwordx4 v[210:213], v[224:225], off
	global_load_dwordx4 v[218:221], v[224:225], off offset:512
	s_mov_b32 s4, 0x170000
	v_lshl_add_u64 v[226:227], v[146:147], 0, s[4:5]
	global_load_dwordx4 v[214:217], v[226:227], off
	global_load_dwordx4 v[150:153], v[226:227], off offset:512
	s_waitcnt vmcnt(12)
;     __device__ __forceinline__ void operator()(const f32x4 (&acc)[2][2][4][2], const pg8::Unit& u, int wr, int wc, int fr, int fq) const {
;         const int row0 = u.pm * 256 + wr * 64 + fr; const int colb = u.pn * 256 + 32 * wc + 8 * fq;
;         if (u.nt == 0) {
; #pragma unroll
;             for (int ai = 0; ai < 2; ++ai) {
;                 f32x4 xv[4][2][2];
; #pragma unroll
;                 for (int m = 0; m < 4; ++m)
; #pragma unroll
;                     for (int bj = 0; bj < 2; ++bj) { const float* xr = out + (size_t)(row0 + ai * 128 + m * 16) * DM + colb + 128 * bj; xv[m][bj][0] = *(const f32x4*)xr; xv[m][bj][1] = *(const f32x4*)(xr + 4); }
; #pragma unroll
;                 for (int m = 0; m < 4; ++m) {
;                     float* orow = out + (size_t)(row0 + ai * 128 + m * 16) * DM;
; #pragma unroll
;                     for (int bj = 0; bj < 2; ++bj) {
;                         const int col = colb + 128 * bj;
;                         *(f32x4*)(orow + col) = acc[ai][bj][m][0] + xv[m][bj][0]; *(f32x4*)(orow + col + 4) = acc[ai][bj][m][1] + xv[m][bj][1];
;                     }
;                 }
;             }
	v_pk_add_f32 v[60:61], v[60:61], v[160:161]
	v_pk_add_f32 v[62:63], v[62:63], v[162:163]
	v_pk_add_f32 v[56:57], v[56:57], v[164:165]
	v_pk_add_f32 v[58:59], v[58:59], v[166:167]
	v_pk_add_f32 v[52:53], v[52:53], v[168:169]
	v_pk_add_f32 v[54:55], v[54:55], v[170:171]
	v_pk_add_f32 v[48:49], v[48:49], v[172:173]
	v_pk_add_f32 v[50:51], v[50:51], v[174:175]
	s_waitcnt vmcnt(8)
	v_pk_add_f32 v[44:45], v[44:45], v[176:177]
	v_pk_add_f32 v[46:47], v[46:47], v[178:179]
	v_pk_add_f32 v[40:41], v[40:41], v[180:181]
	v_pk_add_f32 v[42:43], v[42:43], v[182:183]
	v_pk_add_f32 v[36:37], v[36:37], v[184:185]
	v_pk_add_f32 v[38:39], v[38:39], v[186:187]
	v_pk_add_f32 v[32:33], v[32:33], v[190:191]
	v_pk_add_f32 v[34:35], v[34:35], v[192:193]
	s_waitcnt vmcnt(4)
	v_pk_add_f32 v[28:29], v[28:29], v[194:195]
	v_pk_add_f32 v[30:31], v[30:31], v[196:197]
	v_pk_add_f32 v[24:25], v[24:25], v[198:199]
	v_pk_add_f32 v[26:27], v[26:27], v[200:201]
	v_pk_add_f32 v[20:21], v[20:21], v[202:203]
	v_pk_add_f32 v[22:23], v[22:23], v[204:205]
	v_pk_add_f32 v[16:17], v[16:17], v[206:207]
	v_pk_add_f32 v[18:19], v[18:19], v[208:209]
	s_waitcnt vmcnt(0)
	v_pk_add_f32 v[12:13], v[12:13], v[210:211]
	v_pk_add_f32 v[14:15], v[14:15], v[212:213]
	v_pk_add_f32 v[8:9], v[8:9], v[214:215]
	v_pk_add_f32 v[10:11], v[10:11], v[216:217]
	v_pk_add_f32 v[4:5], v[4:5], v[218:219]
	v_pk_add_f32 v[6:7], v[6:7], v[220:221]
	v_pk_add_f32 v[0:1], v[0:1], v[150:151]
	v_pk_add_f32 v[2:3], v[2:3], v[152:153]
	s_mov_b32 s4, 0x100000
	v_lshl_add_u64 v[224:225], v[146:147], 0, s[4:5]
	global_store_dwordx4 v[224:225], v[60:63], off
	global_store_dwordx4 v[224:225], v[52:55], off offset:512
	s_mov_b32 s4, 0x110000
	v_lshl_add_u64 v[226:227], v[146:147], 0, s[4:5]
	global_store_dwordx4 v[226:227], v[56:59], off
	global_store_dwordx4 v[226:227], v[48:51], off offset:512
	s_mov_b32 s4, 0x120000
	v_lshl_add_u64 v[224:225], v[146:147], 0, s[4:5]
	global_store_dwordx4 v[224:225], v[44:47], off
	global_store_dwordx4 v[224:225], v[36:39], off offset:512
	s_mov_b32 s4, 0x130000
	v_lshl_add_u64 v[226:227], v[146:147], 0, s[4:5]
	global_store_dwordx4 v[226:227], v[40:43], off
	global_store_dwordx4 v[226:227], v[32:35], off offset:512
	s_mov_b32 s4, 0x140000
	v_lshl_add_u64 v[224:225], v[146:147], 0, s[4:5]
	global_store_dwordx4 v[224:225], v[28:31], off
	global_store_dwordx4 v[224:225], v[20:23], off offset:512
	s_mov_b32 s4, 0x150000
	v_lshl_add_u64 v[226:227], v[146:147], 0, s[4:5]
	global_store_dwordx4 v[226:227], v[24:27], off
	global_store_dwordx4 v[226:227], v[16:19], off offset:512
	s_mov_b32 s4, 0x160000
	v_lshl_add_u64 v[224:225], v[146:147], 0, s[4:5]
	global_store_dwordx4 v[224:225], v[12:15], off
	global_store_dwordx4 v[224:225], v[4:7], off offset:512
	s_mov_b32 s4, 0x170000
	v_lshl_add_u64 v[226:227], v[146:147], 0, s[4:5]
	global_store_dwordx4 v[226:227], v[8:11], off
	global_store_dwordx4 v[226:227], v[0:3], off offset:512
	v_readlane_b32 s4, v254, 16
	v_readlane_b32 s5, v254, 17
	v_readlane_b32 s6, v254, 18
	v_readlane_b32 s7, v254, 19
	v_readlane_b32 s8, v254, 20
	v_readlane_b32 s9, v254, 21
	v_readlane_b32 s10, v254, 22
	v_readlane_b32 s11, v254, 23
	v_readlane_b32 s12, v254, 24
	v_readlane_b32 s13, v254, 25
	v_readlane_b32 s14, v254, 26
	v_readlane_b32 s15, v254, 27
	v_readlane_b32 s16, v254, 28
	v_readlane_b32 s17, v254, 29
	s_and_b64 vcc, exec, s[2:3]
	s_mov_b64 s[2:3], -1
	s_cbranch_vccnz .LBB0_784
